# remove 126 redundant canonicalize v_max in P5 epilogue (relu follows)
# baseline (speedup 1.0000x reference)
.LBB0_1138:
	ds_read_b32 v141, v143
	v_max_f32_e32 v128, 0, v128
	v_max_f32_e32 v124, 0, v124
	v_max_f32_e32 v129, 0, v129
	v_max_f32_e32 v125, 0, v125
	v_max_f32_e32 v130, 0, v130
	v_max_f32_e32 v126, 0, v126
	v_max_f32_e32 v131, 0, v131
	v_max_f32_e32 v127, 0, v127
	v_max_f32_e32 v120, 0, v120
	v_max_f32_e32 v116, 0, v116
	v_max_f32_e32 v121, 0, v121
	v_max_f32_e32 v117, 0, v117
	v_max_f32_e32 v122, 0, v122
	v_max_f32_e32 v118, 0, v118
	v_max_f32_e32 v123, 0, v123
	v_max_f32_e32 v119, 0, v119
	v_lshl_add_u32 v140, s64, 8, v142
	v_mul_f32_e32 v128, v128, v128
	v_mul_f32_e32 v124, v124, v124
	v_mul_f32_e32 v129, v129, v129
	v_mul_f32_e32 v125, v125, v125
	v_mul_f32_e32 v130, v130, v130
	v_mul_f32_e32 v126, v126, v126
	v_mul_f32_e32 v131, v131, v131
	v_mul_f32_e32 v127, v127, v127
	v_mul_f32_e32 v120, v120, v120
	v_mul_f32_e32 v116, v116, v116
	v_mul_f32_e32 v121, v121, v121
	v_mul_f32_e32 v117, v117, v117
	v_mul_f32_e32 v122, v122, v122
	v_mul_f32_e32 v118, v118, v118
	v_mul_f32_e32 v123, v123, v123
	v_mul_f32_e32 v119, v119, v119
	s_waitcnt lgkmcnt(0)
	v_mul_f32_e32 v128, v128, v141
	v_mul_f32_e32 v124, v124, v141
	v_mul_f32_e32 v129, v129, v141
	v_mul_f32_e32 v125, v125, v141
	v_mul_f32_e32 v130, v130, v141
	v_mul_f32_e32 v126, v126, v141
	v_mul_f32_e32 v131, v131, v141
	v_mul_f32_e32 v127, v127, v141
	v_mul_f32_e32 v120, v120, v141
	v_mul_f32_e32 v116, v116, v141
	v_mul_f32_e32 v121, v121, v141
	v_mul_f32_e32 v117, v117, v141
	v_mul_f32_e32 v122, v122, v141
	v_mul_f32_e32 v118, v118, v141
	v_mul_f32_e32 v123, v123, v141
	v_mul_f32_e32 v119, v119, v141
	v_ashrrev_i32_e32 v141, 31, v140
	v_lshl_or_b32 v138, s66, 8, v144
	v_cvt_pk_bf16_f32 v128, v128, v129
	v_cvt_pk_bf16_f32 v129, v130, v131
	v_cvt_pk_bf16_f32 v130, v124, v125
	v_cvt_pk_bf16_f32 v131, v126, v127
	v_cvt_pk_bf16_f32 v120, v120, v121
	v_cvt_pk_bf16_f32 v121, v122, v123
	v_cvt_pk_bf16_f32 v122, v116, v117
	v_lshlrev_b64 v[116:117], 13, v[140:141]
	v_ashrrev_i32_e32 v139, 31, v138
	v_lshl_add_u64 v[116:117], s[30:31], 0, v[116:117]
	v_cvt_pk_bf16_f32 v123, v118, v119
	v_lshl_add_u64 v[124:125], v[138:139], 1, v[116:117]
	v_mov_b32_e32 v116, 0
	v_mov_b32_e32 v117, 0
	v_mov_b32_e32 v118, 0
	v_mov_b32_e32 v119, 0
	v_mov_b32_dpp v116, v120 row_ror:8 row_mask:0xf bank_mask:0xf
	v_mov_b32_dpp v117, v121 row_ror:8 row_mask:0xf bank_mask:0xf
	v_mov_b32_dpp v118, v122 row_ror:8 row_mask:0xf bank_mask:0xf
	v_mov_b32_dpp v119, v123 row_ror:8 row_mask:0xf bank_mask:0xf
	v_lshl_add_u64 v[126:127], v[124:125], 0, s[46:47]
	v_mov_b32_e32 v120, v128
	v_mov_b32_e32 v121, v129
	v_mov_b32_e32 v122, v130
	v_mov_b32_e32 v123, v131
	s_and_saveexec_b64 s[26:27], s[4:5]
	s_cbranch_execz .LBB0_1140
	v_lshl_add_u64 v[168:169], v[124:125], 0, s[48:49]
	v_mov_b64_e32 v[126:127], v[124:125]
	v_mov_b32_e32 v120, v116
	v_mov_b32_e32 v121, v117
	v_mov_b32_e32 v122, v118
	v_mov_b32_e32 v123, v119
	v_mov_b32_e32 v116, v128
	v_mov_b32_e32 v117, v129
	v_mov_b32_e32 v118, v130
	v_mov_b32_e32 v119, v131
	v_mov_b64_e32 v[124:125], v[168:169]
.LBB0_1140:
	s_or_b64 exec, exec, s[26:27]
	global_store_dwordx4 v[126:127], v[116:119], off
	global_store_dwordx4 v[124:125], v[120:123], off
	ds_read_b32 v116, v143 offset:64
	v_max_f32_e32 v112, 0, v112
	v_max_f32_e32 v113, 0, v113
	v_max_f32_e32 v114, 0, v114
	v_max_f32_e32 v115, 0, v115
	v_max_f32_e32 v104, 0, v104
	v_max_f32_e32 v100, 0, v100
	v_max_f32_e32 v105, 0, v105
	v_max_f32_e32 v106, 0, v106
	v_max_f32_e32 v108, 0, v108
	v_mul_f32_e32 v112, v112, v112
	v_max_f32_e32 v109, 0, v109
	v_mul_f32_e32 v113, v113, v113
	v_max_f32_e32 v110, 0, v110
	v_mul_f32_e32 v114, v114, v114
	v_max_f32_e32 v111, 0, v111
	v_mul_f32_e32 v115, v115, v115
	v_mul_f32_e32 v104, v104, v104
	v_mul_f32_e32 v100, v100, v100
	v_max_f32_e32 v101, 0, v101
	v_mul_f32_e32 v105, v105, v105
	v_mul_f32_e32 v106, v106, v106
	v_max_f32_e32 v107, 0, v107
	s_waitcnt lgkmcnt(0)
	v_mul_f32_e32 v112, v112, v116
	v_mul_f32_e32 v108, v108, v108
	v_mul_f32_e32 v113, v113, v116
	v_mul_f32_e32 v109, v109, v109
	v_mul_f32_e32 v114, v114, v116
	v_mul_f32_e32 v110, v110, v110
	v_mul_f32_e32 v115, v115, v116
	v_mul_f32_e32 v111, v111, v111
	v_mul_f32_e32 v104, v104, v116
	v_mul_f32_e32 v100, v100, v116
	v_mul_f32_e32 v105, v105, v116
	v_mul_f32_e32 v101, v101, v101
	v_mul_f32_e32 v106, v106, v116
	v_mul_f32_e32 v107, v107, v107
	v_mul_f32_e32 v108, v108, v116
	v_mul_f32_e32 v109, v109, v116
	v_mul_f32_e32 v110, v110, v116
	v_mul_f32_e32 v111, v111, v116
	v_cvt_pk_bf16_f32 v112, v112, v113
	v_cvt_pk_bf16_f32 v113, v114, v115
	v_cvt_pk_bf16_f32 v114, v108, v109
	v_cvt_pk_bf16_f32 v115, v110, v111
	v_mul_f32_e32 v101, v101, v116
	v_mul_f32_e32 v107, v107, v116
	v_cvt_pk_bf16_f32 v104, v104, v105
	v_cvt_pk_bf16_f32 v105, v106, v107
	v_cvt_pk_bf16_f32 v106, v100, v101
	v_or_b32_e32 v100, 16, v140
	v_max_f32_e32 v102, 0, v102
	v_max_f32_e32 v103, 0, v103
	v_ashrrev_i32_e32 v101, 31, v100
	v_mul_f32_e32 v102, v102, v102
	v_mul_f32_e32 v103, v103, v103
	v_lshlrev_b64 v[100:101], 13, v[100:101]
	v_mul_f32_e32 v102, v102, v116
	v_mul_f32_e32 v103, v103, v116
	v_lshl_add_u64 v[100:101], s[30:31], 0, v[100:101]
	v_cvt_pk_bf16_f32 v107, v102, v103
	v_lshl_add_u64 v[108:109], v[138:139], 1, v[100:101]
	v_mov_b32_e32 v100, 0
	v_mov_b32_e32 v101, 0
	v_mov_b32_e32 v102, 0
	v_mov_b32_e32 v103, 0
	v_mov_b32_dpp v100, v104 row_ror:8 row_mask:0xf bank_mask:0xf
	v_mov_b32_dpp v101, v105 row_ror:8 row_mask:0xf bank_mask:0xf
	v_mov_b32_dpp v102, v106 row_ror:8 row_mask:0xf bank_mask:0xf
	v_mov_b32_dpp v103, v107 row_ror:8 row_mask:0xf bank_mask:0xf
	v_lshl_add_u64 v[110:111], v[108:109], 0, s[46:47]
	v_mov_b32_e32 v104, v112
	v_mov_b32_e32 v105, v113
	v_mov_b32_e32 v106, v114
	v_mov_b32_e32 v107, v115
	s_and_saveexec_b64 s[26:27], s[4:5]
	s_cbranch_execz .LBB0_1142
	v_lshl_add_u64 v[116:117], v[108:109], 0, s[48:49]
	v_mov_b64_e32 v[110:111], v[108:109]
	v_mov_b32_e32 v104, v100
	v_mov_b32_e32 v105, v101
	v_mov_b32_e32 v106, v102
	v_mov_b32_e32 v107, v103
	v_mov_b32_e32 v100, v112
	v_mov_b32_e32 v101, v113
	v_mov_b32_e32 v102, v114
	v_mov_b32_e32 v103, v115
	v_mov_b64_e32 v[108:109], v[116:117]
.LBB0_1142:
	s_or_b64 exec, exec, s[26:27]
	global_store_dwordx4 v[110:111], v[100:103], off
	global_store_dwordx4 v[108:109], v[104:107], off
	ds_read_b32 v100, v143 offset:128
	v_max_f32_e32 v96, 0, v96
	v_max_f32_e32 v97, 0, v97
	v_max_f32_e32 v98, 0, v98
	v_max_f32_e32 v99, 0, v99
	v_max_f32_e32 v88, 0, v88
	v_max_f32_e32 v84, 0, v84
	v_max_f32_e32 v89, 0, v89
	v_max_f32_e32 v90, 0, v90
	v_max_f32_e32 v92, 0, v92
	v_mul_f32_e32 v96, v96, v96
	v_max_f32_e32 v93, 0, v93
	v_mul_f32_e32 v97, v97, v97
	v_max_f32_e32 v94, 0, v94
	v_mul_f32_e32 v98, v98, v98
	v_max_f32_e32 v95, 0, v95
	v_mul_f32_e32 v99, v99, v99
	v_mul_f32_e32 v88, v88, v88
	v_mul_f32_e32 v84, v84, v84
	v_max_f32_e32 v85, 0, v85
	v_mul_f32_e32 v89, v89, v89
	v_mul_f32_e32 v90, v90, v90
	v_max_f32_e32 v91, 0, v91
	s_waitcnt lgkmcnt(0)
	v_mul_f32_e32 v96, v96, v100
	v_mul_f32_e32 v92, v92, v92
	v_mul_f32_e32 v97, v97, v100
	v_mul_f32_e32 v93, v93, v93
	v_mul_f32_e32 v98, v98, v100
	v_mul_f32_e32 v94, v94, v94
	v_mul_f32_e32 v99, v99, v100
	v_mul_f32_e32 v95, v95, v95
	v_mul_f32_e32 v88, v88, v100
	v_mul_f32_e32 v84, v84, v100
	v_mul_f32_e32 v89, v89, v100
	v_mul_f32_e32 v85, v85, v85
	v_mul_f32_e32 v90, v90, v100
	v_mul_f32_e32 v91, v91, v91
	v_mul_f32_e32 v92, v92, v100
	v_mul_f32_e32 v93, v93, v100
	v_mul_f32_e32 v94, v94, v100
	v_mul_f32_e32 v95, v95, v100
	v_cvt_pk_bf16_f32 v96, v96, v97
	v_cvt_pk_bf16_f32 v97, v98, v99
	v_cvt_pk_bf16_f32 v98, v92, v93
	v_cvt_pk_bf16_f32 v99, v94, v95
	v_mul_f32_e32 v85, v85, v100
	v_mul_f32_e32 v91, v91, v100
	v_cvt_pk_bf16_f32 v88, v88, v89
	v_cvt_pk_bf16_f32 v89, v90, v91
	v_cvt_pk_bf16_f32 v90, v84, v85
	v_or_b32_e32 v84, 32, v140
	v_max_f32_e32 v86, 0, v86
	v_max_f32_e32 v87, 0, v87
	v_ashrrev_i32_e32 v85, 31, v84
	v_mul_f32_e32 v86, v86, v86
	v_mul_f32_e32 v87, v87, v87
	v_lshlrev_b64 v[84:85], 13, v[84:85]
	v_mul_f32_e32 v86, v86, v100
	v_mul_f32_e32 v87, v87, v100
	v_lshl_add_u64 v[84:85], s[30:31], 0, v[84:85]
	v_cvt_pk_bf16_f32 v91, v86, v87
	v_lshl_add_u64 v[92:93], v[138:139], 1, v[84:85]
	v_mov_b32_e32 v84, 0
	v_mov_b32_e32 v85, 0
	v_mov_b32_e32 v86, 0
	v_mov_b32_e32 v87, 0
	v_mov_b32_dpp v84, v88 row_ror:8 row_mask:0xf bank_mask:0xf
	v_mov_b32_dpp v85, v89 row_ror:8 row_mask:0xf bank_mask:0xf
	v_mov_b32_dpp v86, v90 row_ror:8 row_mask:0xf bank_mask:0xf
	v_mov_b32_dpp v87, v91 row_ror:8 row_mask:0xf bank_mask:0xf
	v_lshl_add_u64 v[94:95], v[92:93], 0, s[46:47]
	v_mov_b32_e32 v88, v96
	v_mov_b32_e32 v89, v97
	v_mov_b32_e32 v90, v98
	v_mov_b32_e32 v91, v99
	s_and_saveexec_b64 s[26:27], s[4:5]
	s_cbranch_execz .LBB0_1144
	v_lshl_add_u64 v[100:101], v[92:93], 0, s[48:49]
	v_mov_b64_e32 v[94:95], v[92:93]
	v_mov_b32_e32 v88, v84
	v_mov_b32_e32 v89, v85
	v_mov_b32_e32 v90, v86
	v_mov_b32_e32 v91, v87
	v_mov_b32_e32 v84, v96
	v_mov_b32_e32 v85, v97
	v_mov_b32_e32 v86, v98
	v_mov_b32_e32 v87, v99
	v_mov_b64_e32 v[92:93], v[100:101]
.LBB0_1144:
	s_or_b64 exec, exec, s[26:27]
	global_store_dwordx4 v[94:95], v[84:87], off
	global_store_dwordx4 v[92:93], v[88:91], off
	ds_read_b32 v84, v143 offset:192
	v_max_f32_e32 v80, 0, v80
	v_max_f32_e32 v81, 0, v81
	v_max_f32_e32 v82, 0, v82
	v_max_f32_e32 v83, 0, v83
	v_max_f32_e32 v72, 0, v72
	v_max_f32_e32 v68, 0, v68
	v_max_f32_e32 v73, 0, v73
	v_max_f32_e32 v74, 0, v74
	v_max_f32_e32 v76, 0, v76
	v_mul_f32_e32 v80, v80, v80
	v_max_f32_e32 v77, 0, v77
	v_mul_f32_e32 v81, v81, v81
	v_max_f32_e32 v78, 0, v78
	v_mul_f32_e32 v82, v82, v82
	v_max_f32_e32 v79, 0, v79
	v_mul_f32_e32 v83, v83, v83
	v_mul_f32_e32 v72, v72, v72
	v_mul_f32_e32 v68, v68, v68
	v_max_f32_e32 v69, 0, v69
	v_mul_f32_e32 v73, v73, v73
	v_mul_f32_e32 v74, v74, v74
	v_max_f32_e32 v75, 0, v75
	s_waitcnt lgkmcnt(0)
	v_mul_f32_e32 v80, v80, v84
	v_mul_f32_e32 v76, v76, v76
	v_mul_f32_e32 v81, v81, v84
	v_mul_f32_e32 v77, v77, v77
	v_mul_f32_e32 v82, v82, v84
	v_mul_f32_e32 v78, v78, v78
	v_mul_f32_e32 v83, v83, v84
	v_mul_f32_e32 v79, v79, v79
	v_mul_f32_e32 v72, v72, v84
	v_mul_f32_e32 v68, v68, v84
	v_mul_f32_e32 v73, v73, v84
	v_mul_f32_e32 v69, v69, v69
	v_mul_f32_e32 v74, v74, v84
	v_mul_f32_e32 v75, v75, v75
	v_mul_f32_e32 v76, v76, v84
	v_mul_f32_e32 v77, v77, v84
	v_mul_f32_e32 v78, v78, v84
	v_mul_f32_e32 v79, v79, v84
	v_cvt_pk_bf16_f32 v80, v80, v81
	v_cvt_pk_bf16_f32 v81, v82, v83
	v_cvt_pk_bf16_f32 v82, v76, v77
	v_cvt_pk_bf16_f32 v83, v78, v79
	v_mul_f32_e32 v69, v69, v84
	v_mul_f32_e32 v75, v75, v84
	v_cvt_pk_bf16_f32 v72, v72, v73
	v_cvt_pk_bf16_f32 v73, v74, v75
	v_cvt_pk_bf16_f32 v74, v68, v69
	v_or_b32_e32 v68, 48, v140
	v_max_f32_e32 v70, 0, v70
	v_max_f32_e32 v71, 0, v71
	v_ashrrev_i32_e32 v69, 31, v68
	v_mul_f32_e32 v70, v70, v70
	v_mul_f32_e32 v71, v71, v71
	v_lshlrev_b64 v[68:69], 13, v[68:69]
	v_mul_f32_e32 v70, v70, v84
	v_mul_f32_e32 v71, v71, v84
	v_lshl_add_u64 v[68:69], s[30:31], 0, v[68:69]
	v_cvt_pk_bf16_f32 v75, v70, v71
	v_lshl_add_u64 v[76:77], v[138:139], 1, v[68:69]
	v_mov_b32_e32 v68, 0
	v_mov_b32_e32 v69, 0
	v_mov_b32_e32 v70, 0
	v_mov_b32_e32 v71, 0
	v_mov_b32_dpp v68, v72 row_ror:8 row_mask:0xf bank_mask:0xf
	v_mov_b32_dpp v69, v73 row_ror:8 row_mask:0xf bank_mask:0xf
	v_mov_b32_dpp v70, v74 row_ror:8 row_mask:0xf bank_mask:0xf
	v_mov_b32_dpp v71, v75 row_ror:8 row_mask:0xf bank_mask:0xf
	v_lshl_add_u64 v[78:79], v[76:77], 0, s[46:47]
	v_mov_b32_e32 v72, v80
	v_mov_b32_e32 v73, v81
	v_mov_b32_e32 v74, v82
	v_mov_b32_e32 v75, v83
	s_and_saveexec_b64 s[26:27], s[4:5]
	s_cbranch_execz .LBB0_1146
	v_lshl_add_u64 v[84:85], v[76:77], 0, s[48:49]
	v_mov_b64_e32 v[78:79], v[76:77]
	v_mov_b32_e32 v72, v68
	v_mov_b32_e32 v73, v69
	v_mov_b32_e32 v74, v70
	v_mov_b32_e32 v75, v71
	v_mov_b32_e32 v68, v80
	v_mov_b32_e32 v69, v81
	v_mov_b32_e32 v70, v82
	v_mov_b32_e32 v71, v83
	v_mov_b64_e32 v[76:77], v[84:85]
.LBB0_1146:
	s_or_b64 exec, exec, s[26:27]
	global_store_dwordx4 v[78:79], v[68:71], off
	global_store_dwordx4 v[76:77], v[72:75], off
	ds_read_b32 v70, v143 offset:512
	v_max_f32_e32 v66, 0, v66
	v_mul_f32_e32 v66, v66, v66
	s_waitcnt lgkmcnt(0)
	v_mul_f32_e32 v68, v66, v70
	v_max_f32_e32 v66, v67, v67
	v_max_f32_e32 v66, 0, v66
	v_max_f32_e32 v56, 0, v56
	v_max_f32_e32 v52, 0, v52
	v_max_f32_e32 v57, 0, v57
	v_max_f32_e32 v53, 0, v53
	v_max_f32_e32 v58, 0, v58
	v_max_f32_e32 v64, 0, v64
	v_max_f32_e32 v60, 0, v60
	v_max_f32_e32 v65, 0, v65
	v_max_f32_e32 v61, 0, v61
	v_max_f32_e32 v62, 0, v62
	v_max_f32_e32 v63, 0, v63
	v_mul_f32_e32 v66, v66, v66
	v_mul_f32_e32 v56, v56, v56
	v_mul_f32_e32 v52, v52, v52
	v_mul_f32_e32 v57, v57, v57
	v_mul_f32_e32 v53, v53, v53
	v_mul_f32_e32 v58, v58, v58
	v_max_f32_e32 v59, 0, v59
	v_mul_f32_e32 v64, v64, v64
	v_mul_f32_e32 v60, v60, v60
	v_mul_f32_e32 v65, v65, v65
	v_mul_f32_e32 v61, v61, v61
	v_mul_f32_e32 v62, v62, v62
	v_mul_f32_e32 v67, v66, v70
	v_mul_f32_e32 v63, v63, v63
	v_mul_f32_e32 v56, v56, v70
	v_mul_f32_e32 v52, v52, v70
	v_mul_f32_e32 v57, v57, v70
	v_mul_f32_e32 v53, v53, v70
	v_mul_f32_e32 v58, v58, v70
	v_mul_f32_e32 v59, v59, v59
	v_mul_f32_e32 v64, v64, v70
	v_mul_f32_e32 v60, v60, v70
	v_mul_f32_e32 v65, v65, v70
	v_mul_f32_e32 v61, v61, v70
	v_mul_f32_e32 v62, v62, v70
	v_mul_f32_e32 v63, v63, v70
	v_cvt_pk_bf16_f32 v66, v64, v65
	v_cvt_pk_bf16_f32 v67, v68, v67
	v_cvt_pk_bf16_f32 v68, v60, v61
	v_cvt_pk_bf16_f32 v69, v62, v63
	v_max_f32_e32 v54, 0, v54
	v_max_f32_e32 v55, 0, v55
	v_mul_f32_e32 v59, v59, v70
	v_cvt_pk_bf16_f32 v56, v56, v57
	v_cvt_pk_bf16_f32 v57, v58, v59
	v_cvt_pk_bf16_f32 v58, v52, v53
	v_lshlrev_b64 v[52:53], 13, v[140:141]
	v_mul_f32_e32 v54, v54, v54
	v_mul_f32_e32 v55, v55, v55
	v_lshl_add_u64 v[52:53], s[30:31], 0, v[52:53]
	v_mul_f32_e32 v54, v54, v70
	v_mul_f32_e32 v55, v55, v70
	v_lshl_add_u64 v[60:61], v[138:139], 1, v[52:53]
	s_mov_b64 s[26:27], 0x100000
	v_cvt_pk_bf16_f32 v59, v54, v55
	v_lshl_add_u64 v[62:63], v[60:61], 0, s[26:27]
	v_mov_b32_e32 v52, 0
	v_mov_b32_e32 v53, 0
	v_mov_b32_e32 v54, 0
	v_mov_b32_e32 v55, 0
	s_mov_b64 s[26:27], 0xf0040
	v_mov_b32_dpp v52, v56 row_ror:8 row_mask:0xf bank_mask:0xf
	v_mov_b32_dpp v53, v57 row_ror:8 row_mask:0xf bank_mask:0xf
	v_mov_b32_dpp v54, v58 row_ror:8 row_mask:0xf bank_mask:0xf
	v_mov_b32_dpp v55, v59 row_ror:8 row_mask:0xf bank_mask:0xf
	v_lshl_add_u64 v[64:65], v[60:61], 0, s[26:27]
	v_mov_b32_e32 v56, v66
	v_mov_b32_e32 v57, v67
	v_mov_b32_e32 v58, v68
	v_mov_b32_e32 v59, v69
	s_and_saveexec_b64 s[26:27], s[4:5]
	s_cbranch_execz .LBB0_1148
	v_lshl_add_u64 v[70:71], v[62:63], 0, s[48:49]
	v_mov_b64_e32 v[64:65], v[62:63]
	v_mov_b32_e32 v56, v52
	v_mov_b32_e32 v57, v53
	v_mov_b32_e32 v58, v54
	v_mov_b32_e32 v59, v55
	v_mov_b32_e32 v52, v66
	v_mov_b32_e32 v53, v67
	v_mov_b32_e32 v54, v68
	v_mov_b32_e32 v55, v69
	v_mov_b64_e32 v[62:63], v[70:71]
.LBB0_1148:
	s_or_b64 exec, exec, s[26:27]
	global_store_dwordx4 v[64:65], v[52:55], off
	global_store_dwordx4 v[62:63], v[56:59], off
	ds_read_b32 v52, v143 offset:576
	v_max_f32_e32 v48, 0, v48
	v_max_f32_e32 v44, 0, v44
	v_max_f32_e32 v49, 0, v49
	v_max_f32_e32 v45, 0, v45
	v_max_f32_e32 v50, 0, v50
	v_max_f32_e32 v51, 0, v51
	v_max_f32_e32 v40, 0, v40
	v_max_f32_e32 v36, 0, v36
	v_max_f32_e32 v41, 0, v41
	v_max_f32_e32 v37, 0, v37
	v_max_f32_e32 v42, 0, v42
	v_max_f32_e32 v38, 0, v38
	v_max_f32_e32 v43, 0, v43
	v_max_f32_e32 v39, 0, v39
	v_mul_f32_e32 v48, v48, v48
	v_mul_f32_e32 v44, v44, v44
	v_mul_f32_e32 v49, v49, v49
	v_mul_f32_e32 v45, v45, v45
	v_max_f32_e32 v46, 0, v46
	v_mul_f32_e32 v50, v50, v50
	v_max_f32_e32 v47, 0, v47
	v_mul_f32_e32 v51, v51, v51
	v_mul_f32_e32 v40, v40, v40
	v_mul_f32_e32 v36, v36, v36
	v_mul_f32_e32 v41, v41, v41
	v_mul_f32_e32 v37, v37, v37
	v_mul_f32_e32 v42, v42, v42
	v_mul_f32_e32 v38, v38, v38
	v_mul_f32_e32 v43, v43, v43
	v_mul_f32_e32 v39, v39, v39
	s_waitcnt lgkmcnt(0)
	v_mul_f32_e32 v48, v48, v52
	v_mul_f32_e32 v44, v44, v52
	v_mul_f32_e32 v49, v49, v52
	v_mul_f32_e32 v45, v45, v52
	v_mul_f32_e32 v50, v50, v52
	v_mul_f32_e32 v46, v46, v46
	v_mul_f32_e32 v51, v51, v52
	v_mul_f32_e32 v47, v47, v47
	v_mul_f32_e32 v40, v40, v52
	v_mul_f32_e32 v36, v36, v52
	v_mul_f32_e32 v41, v41, v52
	v_mul_f32_e32 v37, v37, v52
	v_mul_f32_e32 v42, v42, v52
	v_mul_f32_e32 v38, v38, v52
	v_mul_f32_e32 v43, v43, v52
	v_mul_f32_e32 v39, v39, v52
	s_mov_b64 s[26:27], 0x120000
	v_mul_f32_e32 v46, v46, v52
	v_mul_f32_e32 v47, v47, v52
	v_cvt_pk_bf16_f32 v48, v48, v49
	v_cvt_pk_bf16_f32 v49, v50, v51
	v_cvt_pk_bf16_f32 v50, v44, v45
	v_cvt_pk_bf16_f32 v51, v46, v47
	v_cvt_pk_bf16_f32 v40, v40, v41
	v_cvt_pk_bf16_f32 v41, v42, v43
	v_cvt_pk_bf16_f32 v42, v36, v37
	v_cvt_pk_bf16_f32 v43, v38, v39
	v_lshl_add_u64 v[44:45], v[60:61], 0, s[26:27]
	v_mov_b32_e32 v36, 0
	v_mov_b32_e32 v37, 0
	v_mov_b32_e32 v38, 0
	v_mov_b32_e32 v39, 0
	s_mov_b64 s[26:27], 0x110040
	v_mov_b32_dpp v36, v40 row_ror:8 row_mask:0xf bank_mask:0xf
	v_mov_b32_dpp v37, v41 row_ror:8 row_mask:0xf bank_mask:0xf
	v_mov_b32_dpp v38, v42 row_ror:8 row_mask:0xf bank_mask:0xf
	v_mov_b32_dpp v39, v43 row_ror:8 row_mask:0xf bank_mask:0xf
	v_lshl_add_u64 v[46:47], v[60:61], 0, s[26:27]
	v_mov_b32_e32 v40, v48
	v_mov_b32_e32 v41, v49
	v_mov_b32_e32 v42, v50
	v_mov_b32_e32 v43, v51
	s_and_saveexec_b64 s[26:27], s[4:5]
	s_cbranch_execz .LBB0_1150
	v_lshl_add_u64 v[52:53], v[44:45], 0, s[48:49]
	v_mov_b64_e32 v[46:47], v[44:45]
	v_mov_b32_e32 v40, v36
	v_mov_b32_e32 v41, v37
	v_mov_b32_e32 v42, v38
	v_mov_b32_e32 v43, v39
	v_mov_b32_e32 v36, v48
	v_mov_b32_e32 v37, v49
	v_mov_b32_e32 v38, v50
	v_mov_b32_e32 v39, v51
	v_mov_b64_e32 v[44:45], v[52:53]
.LBB0_1150:
	s_or_b64 exec, exec, s[26:27]
	global_store_dwordx4 v[46:47], v[36:39], off
	global_store_dwordx4 v[44:45], v[40:43], off
	ds_read_b32 v38, v143 offset:640
	v_max_f32_e32 v34, 0, v34
	v_mul_f32_e32 v34, v34, v34
	s_waitcnt lgkmcnt(0)
	v_mul_f32_e32 v36, v34, v38
	v_max_f32_e32 v34, v35, v35
	v_max_f32_e32 v34, 0, v34
	v_max_f32_e32 v24, 0, v24
	v_max_f32_e32 v20, 0, v20
	v_max_f32_e32 v25, 0, v25
	v_max_f32_e32 v21, 0, v21
	v_max_f32_e32 v26, 0, v26
	v_max_f32_e32 v32, 0, v32
	v_max_f32_e32 v28, 0, v28
	v_max_f32_e32 v33, 0, v33
	v_max_f32_e32 v29, 0, v29
	v_max_f32_e32 v30, 0, v30
	v_max_f32_e32 v31, 0, v31
	v_mul_f32_e32 v34, v34, v34
	v_mul_f32_e32 v24, v24, v24
	v_mul_f32_e32 v20, v20, v20
	v_mul_f32_e32 v25, v25, v25
	v_mul_f32_e32 v21, v21, v21
	v_mul_f32_e32 v26, v26, v26
	v_max_f32_e32 v27, 0, v27
	v_mul_f32_e32 v32, v32, v32
	v_mul_f32_e32 v28, v28, v28
	v_mul_f32_e32 v33, v33, v33
	v_mul_f32_e32 v29, v29, v29
	v_mul_f32_e32 v30, v30, v30
	v_mul_f32_e32 v35, v34, v38
	v_mul_f32_e32 v31, v31, v31
	v_mul_f32_e32 v24, v24, v38
	v_mul_f32_e32 v20, v20, v38
	v_mul_f32_e32 v25, v25, v38
	v_mul_f32_e32 v21, v21, v38
	v_max_f32_e32 v22, 0, v22
	v_mul_f32_e32 v26, v26, v38
	v_max_f32_e32 v23, 0, v23
	v_mul_f32_e32 v27, v27, v27
	v_mul_f32_e32 v32, v32, v38
	v_mul_f32_e32 v28, v28, v38
	v_mul_f32_e32 v33, v33, v38
	v_mul_f32_e32 v29, v29, v38
	v_mul_f32_e32 v30, v30, v38
	v_mul_f32_e32 v31, v31, v38
	v_cvt_pk_bf16_f32 v34, v32, v33
	v_cvt_pk_bf16_f32 v35, v36, v35
	v_cvt_pk_bf16_f32 v36, v28, v29
	v_cvt_pk_bf16_f32 v37, v30, v31
	v_mul_f32_e32 v22, v22, v22
	v_mul_f32_e32 v27, v27, v38
	v_mul_f32_e32 v23, v23, v23
	v_cvt_pk_bf16_f32 v24, v24, v25
	v_cvt_pk_bf16_f32 v25, v26, v27
	v_cvt_pk_bf16_f32 v26, v20, v21
	v_lshlrev_b64 v[20:21], 13, v[140:141]
	v_mul_f32_e32 v22, v22, v38
	v_mul_f32_e32 v23, v23, v38
	v_lshl_add_u64 v[20:21], s[30:31], 0, v[20:21]
	v_cvt_pk_bf16_f32 v27, v22, v23
	v_lshl_add_u64 v[28:29], v[138:139], 1, v[20:21]
	s_mov_b64 s[26:27], 0x140000
	v_mov_b32_e32 v20, 0
	v_mov_b32_e32 v21, 0
	v_mov_b32_e32 v22, 0
	v_mov_b32_e32 v23, 0
	v_lshl_add_u64 v[30:31], v[28:29], 0, s[26:27]
	v_mov_b32_dpp v20, v24 row_ror:8 row_mask:0xf bank_mask:0xf
	v_mov_b32_dpp v21, v25 row_ror:8 row_mask:0xf bank_mask:0xf
	v_mov_b32_dpp v22, v26 row_ror:8 row_mask:0xf bank_mask:0xf
	v_mov_b32_dpp v23, v27 row_ror:8 row_mask:0xf bank_mask:0xf
	v_lshl_add_u64 v[32:33], v[28:29], 0, s[50:51]
	v_mov_b32_e32 v24, v34
	v_mov_b32_e32 v25, v35
	v_mov_b32_e32 v26, v36
	v_mov_b32_e32 v27, v37
	s_and_saveexec_b64 s[26:27], s[4:5]
	s_cbranch_execz .LBB0_1152
	v_lshl_add_u64 v[38:39], v[30:31], 0, s[48:49]
	v_mov_b64_e32 v[32:33], v[30:31]
	v_mov_b32_e32 v24, v20
	v_mov_b32_e32 v25, v21
	v_mov_b32_e32 v26, v22
	v_mov_b32_e32 v27, v23
	v_mov_b32_e32 v20, v34
	v_mov_b32_e32 v21, v35
	v_mov_b32_e32 v22, v36
	v_mov_b32_e32 v23, v37
	v_mov_b64_e32 v[30:31], v[38:39]
.LBB0_1152:
	s_or_b64 exec, exec, s[26:27]
	global_store_dwordx4 v[32:33], v[20:23], off
	global_store_dwordx4 v[30:31], v[24:27], off
	ds_read_b32 v20, v143 offset:704
	v_max_f32_e32 v16, 0, v16
	v_max_f32_e32 v17, 0, v17
	v_max_f32_e32 v18, 0, v18
	v_max_f32_e32 v19, 0, v19
	v_max_f32_e32 v8, 0, v8
	v_max_f32_e32 v4, 0, v4
	v_max_f32_e32 v9, 0, v9
	v_max_f32_e32 v5, 0, v5
	v_max_f32_e32 v10, 0, v10
	v_max_f32_e32 v6, 0, v6
	v_max_f32_e32 v11, 0, v11
	v_max_f32_e32 v7, 0, v7
	v_max_f32_e32 v12, 0, v12
	v_mul_f32_e32 v16, v16, v16
	v_max_f32_e32 v13, 0, v13
	v_mul_f32_e32 v17, v17, v17
	v_max_f32_e32 v14, 0, v14
	v_mul_f32_e32 v18, v18, v18
	v_max_f32_e32 v15, 0, v15
	v_mul_f32_e32 v19, v19, v19
	v_mul_f32_e32 v8, v8, v8
	v_mul_f32_e32 v4, v4, v4
	v_mul_f32_e32 v9, v9, v9
	v_mul_f32_e32 v5, v5, v5
	v_mul_f32_e32 v10, v10, v10
	v_mul_f32_e32 v6, v6, v6
	v_mul_f32_e32 v11, v11, v11
	v_mul_f32_e32 v7, v7, v7
	s_waitcnt lgkmcnt(0)
	v_mul_f32_e32 v16, v16, v20
	v_mul_f32_e32 v12, v12, v12
	v_mul_f32_e32 v17, v17, v20
	v_mul_f32_e32 v13, v13, v13
	v_mul_f32_e32 v18, v18, v20
	v_mul_f32_e32 v14, v14, v14
	v_mul_f32_e32 v19, v19, v20
	v_mul_f32_e32 v15, v15, v15
	v_mul_f32_e32 v8, v8, v20
	v_mul_f32_e32 v4, v4, v20
	v_mul_f32_e32 v9, v9, v20
	v_mul_f32_e32 v5, v5, v20
	v_mul_f32_e32 v10, v10, v20
	v_mul_f32_e32 v6, v6, v20
	v_mul_f32_e32 v11, v11, v20
	v_mul_f32_e32 v7, v7, v20
	v_mul_f32_e32 v12, v12, v20
	v_mul_f32_e32 v13, v13, v20
	v_mul_f32_e32 v14, v14, v20
	v_mul_f32_e32 v15, v15, v20
	v_cvt_pk_bf16_f32 v16, v16, v17
	v_cvt_pk_bf16_f32 v17, v18, v19
	v_cvt_pk_bf16_f32 v18, v12, v13
	v_cvt_pk_bf16_f32 v19, v14, v15
	v_cvt_pk_bf16_f32 v8, v8, v9
	v_cvt_pk_bf16_f32 v9, v10, v11
	v_cvt_pk_bf16_f32 v10, v4, v5
	v_cvt_pk_bf16_f32 v11, v6, v7
	v_mov_b32_e32 v4, 0
	v_mov_b32_e32 v5, 0
	v_mov_b32_e32 v6, 0
	v_mov_b32_e32 v7, 0
	v_lshl_add_u64 v[12:13], v[28:29], 0, s[52:53]
	v_mov_b32_dpp v4, v8 row_ror:8 row_mask:0xf bank_mask:0xf
	v_mov_b32_dpp v5, v9 row_ror:8 row_mask:0xf bank_mask:0xf
	v_mov_b32_dpp v6, v10 row_ror:8 row_mask:0xf bank_mask:0xf
	v_mov_b32_dpp v7, v11 row_ror:8 row_mask:0xf bank_mask:0xf
	v_lshl_add_u64 v[14:15], v[28:29], 0, s[54:55]
	v_mov_b32_e32 v8, v16
	v_mov_b32_e32 v9, v17
	v_mov_b32_e32 v10, v18
	v_mov_b32_e32 v11, v19
	s_and_saveexec_b64 s[26:27], s[4:5]
	s_cbranch_execz .LBB0_1154
	v_lshl_add_u64 v[20:21], v[12:13], 0, s[48:49]
	v_mov_b64_e32 v[14:15], v[12:13]
	v_mov_b32_e32 v8, v4
	v_mov_b32_e32 v9, v5
	v_mov_b32_e32 v10, v6
	v_mov_b32_e32 v11, v7
	v_mov_b32_e32 v4, v16
	v_mov_b32_e32 v5, v17
	v_mov_b32_e32 v6, v18
	v_mov_b32_e32 v7, v19
	v_mov_b64_e32 v[12:13], v[20:21]
